# final norm: sample rows spread over all workgroups as well
# speedup vs baseline: 1.0112x; 1.0112x over previous
; __device__ __forceinline__ void phase_norm(PP P, int l, int which, int nsl, const float* fgate, float fscale, const Ids I) {
;     ...
;     for (int row0 = gw; row0 < MT; row0 += 2 * nw) {
;         const int rows[2] = {row0, (row0 + nw < MT) ? row0 + nw : row0};
;         f32x4 v[2][4]; float ss[2];
; #pragma unroll
;         for (int j = 0; j < 2; ++j) { const int row = rows[j];
;             const float* xr = from_in ? (row < MTP ? P->in[I_XP] + (size_t)row * D : P->in[I_XS] + (size_t)(row - MTP) * D) : xb + (size_t)row * D;
; #pragma unroll
;             for (int i = 0; i < 4; ++i) v[j][i] = *(const f32x4*)(xr + lane * 4 + 256 * i);
;             if (nsl > 0 && row >= MTP && !(j == 1 && row == row0)) {
.LBB0_20:
	s_add_i32 s54, s54, s2
	v_lshl_add_u64 v[44:45], v[44:45], 0, s[4:5]
	s_cmp_lt_i32 s54, 0
	s_cbranch_scc1 .LBB0_21
	s_cmpk_gt_i32 s54, 0x7ff
	s_cbranch_scc1 .LBB0_43
	s_and_b32 s3, s54, 3
	s_cmp_lg_u32 s3, 0
	s_cbranch_scc1 .LBB0_43
	s_lshr_b32 s6, s54, 2
	s_sub_i32 s6, s6, s54
	s_ashr_i32 s7, s6, 31
	s_lshl_b64 s[6:7], s[6:7], 12
	s_lshr_b32 s54, s54, 2
	v_lshl_add_u64 v[44:45], v[44:45], 0, s[6:7]
